# no grid barrier between the last scan segment and the gates GEMM (the GEMM reads only phase-1 outputs)
# speedup vs baseline: 1.0119x; 1.0119x over previous
.LBB0_752:
	s_cmpk_lt_i32 s10, 0x3e8
	s_cbranch_scc0 .LBB0_806
	s_waitcnt vmcnt(0)
	s_waitcnt lgkmcnt(0)
	s_barrier
	s_cmp_eq_u32 s10, 4
	s_cbranch_scc1 .Ltramp_b45
	s_cmp_eq_u32 s10, 13
	s_cbranch_scc1 .Ltramp_b45
	s_mov_b64 s[0:1], exec
	v_readlane_b32 s16, v250, 3
	v_readlane_b32 s17, v250, 4
	s_and_b64 s[16:17], s[0:1], s[16:17]
	s_mov_b64 exec, s[16:17]
	s_cbranch_execz .LBB0_805
	v_readlane_b32 s2, v254, 20
	s_waitcnt vmcnt(0) expcnt(0) lgkmcnt(0)
	s_nop 0
	v_mov_b32_e32 v0, s2
	ds_read_b32 v3, v0
	v_readlane_b32 s2, v254, 21
	s_waitcnt lgkmcnt(0)
	v_cmp_ne_u32_e32 vcc, 0, v3
	v_mov_b32_e32 v0, s2
	ds_read_b32 v2, v0
	s_cbranch_vccnz .LBB0_769
	s_mov_b32 s2, 1
	s_branch .LBB0_757
